# K/V staging LDS write offset kept in v235 instead of recomputed per tile (5 tile loops)
# speedup vs baseline: 1.0058x; 1.0058x over previous
; DI int tidx() { int t = threadIdx.x; asm volatile("" : "+v"(t)); return t; }
; DI void task_attnA(const P& p, int layer, int task, bf16_t* sm, int dm) {
;     ...
;     const float lam = ((const float*)(p.ws + O_LAM))[layer];
;     const float li = 0.8f - 0.6f * expf(-0.3f * (float)layer);
;     float ss = 0.f;
; DI void kv_lstore(const KVRegs& r, bf16_t* Kl, bf16_t* Vl) {
;   const int c0 = tidx();
;   *(u32x4*)(Kl + (c0 >> 3) * 72 + (c0 & 7) * 8) = r.k0;
;   *(u32x4*)(Vl + (c0 >> 3) * 72 + (c0 & 7) * 8) = r.v0;
.LBB0_637:
	s_or_b64 exec, exec, s[0:1]
	v_cvt_f32_u32_e32 v0, s26
	s_mov_b32 s2, 0x3fb8aa3b
	s_lshl_b32 s66, s26, 6
	s_lshl_b64 s[0:1], s[66:67], 2
	v_mul_f32_e32 v0, 0xbe99999a, v0
	v_mul_f32_e32 v1, 0x3fb8aa3b, v0
	v_fma_f32 v2, v0, s2, -v1
	v_rndne_f32_e32 v3, v1
	v_fmac_f32_e32 v2, 0x32a5705f, v0
	v_sub_f32_e32 v1, v1, v3
	v_add_f32_e32 v1, v1, v2
	v_exp_f32_e32 v1, v1
	v_cvt_i32_f32_e32 v2, v3
	v_readlane_b32 s2, v253, 32
	s_add_u32 s62, s2, s0
	v_readlane_b32 s0, v253, 33
	s_addc_u32 s63, s0, s1
	s_lshl_b32 s0, s26, 3
	v_writelane_b32 v255, s0, 15
	s_mov_b32 s0, 0xc2ce8ed0
	v_ldexp_f32 v1, v1, v2
	v_cmp_ngt_f32_e32 vcc, s0, v0
	s_mov_b32 s0, 0x42b17218
	s_lshl_b32 s4, s26, 11
	v_cndmask_b32_e32 v1, 0, v1, vcc
	v_cmp_nlt_f32_e32 vcc, s0, v0
	s_lshl_b32 s66, s26, 7
	s_lshl_b64 s[0:1], s[26:27], 21
	s_lshl_b64 s[2:3], s[26:27], 17
	v_writelane_b32 v255, s4, 21
	s_lshl_b64 s[4:5], s[26:27], 2
	v_readlane_b32 s6, v254, 32
	s_add_u32 s6, s6, s4
	v_readlane_b32 s4, v254, 33
	v_readlane_b32 s36, v253, 6
	s_addc_u32 s7, s4, s5
	s_lshl_b64 s[4:5], s[66:67], 2
	v_readlane_b32 s44, v253, 14
	v_readlane_b32 s45, v253, 15
	s_add_u32 s26, s44, s4
	v_writelane_b32 v255, s6, 23
	s_addc_u32 s27, s45, s5
	v_readlane_b32 s4, v254, 34
	v_writelane_b32 v255, s7, 24
	s_add_u32 s0, s4, s0
	v_writelane_b32 v255, s0, 19
	v_readlane_b32 s0, v254, 35
	v_mov_b32_e32 v0, 0x7f800000
	s_addc_u32 s0, s0, s1
	v_cndmask_b32_e32 v0, v0, v1, vcc
	v_mov_b32_e32 v1, 0xbf4ccccd
	v_writelane_b32 v255, s0, 17
	v_readlane_b32 s0, v254, 40
	v_fmamk_f32 v0, v0, 0x3f19999a, v1
	s_add_u32 s60, s0, s2
	v_readlane_b32 s0, v254, 41
	s_waitcnt vmcnt(24)
	v_add_f32_e32 v136, 1.0, v0
	s_addc_u32 s22, s0, s3
	s_barrier
	v_readlane_b32 s37, v253, 7
	v_readlane_b32 s38, v253, 8
	v_readlane_b32 s39, v253, 9
	v_readlane_b32 s40, v253, 10
	v_readlane_b32 s41, v253, 11
	v_readlane_b32 s42, v253, 12
	v_readlane_b32 s43, v253, 13
	v_readlane_b32 s46, v253, 16
	v_readlane_b32 s47, v253, 17
	v_readlane_b32 s48, v253, 18
	v_readlane_b32 s49, v253, 19
	v_readlane_b32 s50, v253, 20
	v_readlane_b32 s51, v253, 21
	v_lshrrev_b32_e32 v235, 3, v195
	v_and_b32_e32 v222, 7, v195
	v_mul_u32_u24_e32 v235, 0x90, v235
	v_lshl_add_u32 v235, v222, 4, v235
	s_branch .LBB0_642

; DI int tidx() { int t = threadIdx.x; asm volatile("" : "+v"(t)); return t; }
; DI void kv_lstore(const KVRegs& r, bf16_t* Kl, bf16_t* Vl) {
;   const int c0 = tidx();
;   *(u32x4*)(Kl + (c0 >> 3) * 72 + (c0 & 7) * 8) = r.k0;
;   *(u32x4*)(Vl + (c0 >> 3) * 72 + (c0 & 7) * 8) = r.v0;
; DI void task_nsa(const P& p, int layer, int task, bf16_t* sm, int dm) {
;     ...
;     for (int ct = 0; ct < nct; ++ct, ++itc) {
;       bf16_t* Kl = sm + (itc & 1) * 9216; bf16_t* Vl = Kl + 4608;
;       kv_lstore(R, Kl, Vl);
;       if (ct + 1 < nct) kv_gload(R, kg, 64, vg, 256, (ct + 1) * 64);
;       __syncthreads();
.LBB0_666:
	v_mov_b32_e32 v32, v195
	s_bitcmp1_b32 s4, 0
	s_cselect_b32 s7, 0x4800, 0
	s_add_i32 s7, s7, 0
	s_add_i32 s4, s4, 1
	v_add_u32_e32 v32, s7, v235
	s_cmp_ge_u32 s4, s39
	s_waitcnt vmcnt(0)
	ds_write_b128 v32, v[80:83]
	ds_write_b128 v32, v[84:87] offset:9216
	s_cbranch_scc1 .LBB0_668
	v_mov_b32_e32 v36, v195
	s_nop 0
	v_ashrrev_i32_e32 v32, 3, v36
	v_add_u32_e32 v34, s6, v32
	v_ashrrev_i32_e32 v35, 31, v34
	v_lshlrev_b64 v[34:35], 7, v[34:35]
	v_lshlrev_b32_e32 v33, 4, v36
	v_lshl_add_u64 v[34:35], s[28:29], 0, v[34:35]
	v_and_b32_e32 v192, 0x70, v33
	v_lshl_add_u64 v[34:35], v[34:35], 0, v[192:193]
	v_ashrrev_i32_e32 v33, 31, v32
	global_load_dwordx4 v[80:83], v[34:35], off
	v_lshlrev_b64 v[32:33], 9, v[32:33]
	v_and_b32_e32 v34, 7, v36
	v_lshl_or_b32 v32, v34, 4, v32
	v_lshl_add_u64 v[32:33], s[2:3], 0, v[32:33]
	global_load_dwordx4 v[84:87], v[32:33], off

; DI void task_nsa(const P& p, int layer, int task, bf16_t* sm, int dm) {
;     ...
;     for (int ct = 0; ct < nct; ++ct, ++itc) {
;       bf16_t* Kl = sm + (itc & 1) * 9216; bf16_t* Vl = Kl + 4608;
;       kv_lstore(R, Kl, Vl);
;       if (ct + 1 < nct) kv_gload(R, kg, 64, vg, 256, (ct + 1) * 64);
;       __syncthreads();
.LBB0_674:
	s_add_i32 s0, s39, s47
	v_mov_b32_e32 v0, v195
	s_bitcmp1_b32 s0, 0
	s_cselect_b32 s0, 0x4800, 0
	s_add_i32 s0, s0, 0
	s_add_i32 s47, s47, 1
	v_add_u32_e32 v0, s0, v235
	s_cmp_ge_u32 s47, s39
	s_waitcnt vmcnt(0)
	ds_write_b128 v0, v[16:19]
	ds_write_b128 v0, v[20:23] offset:9216
	s_cbranch_scc1 .LBB0_676
	v_mov_b32_e32 v4, v195
	s_nop 0
	v_ashrrev_i32_e32 v0, 3, v4
	v_add_u32_e32 v2, s48, v0
	v_ashrrev_i32_e32 v3, 31, v2
	v_lshlrev_b64 v[2:3], 7, v[2:3]
	v_lshlrev_b32_e32 v1, 4, v4
	v_lshl_add_u64 v[2:3], s[28:29], 0, v[2:3]
	v_and_b32_e32 v192, 0x70, v1
	v_lshl_add_u64 v[2:3], v[2:3], 0, v[192:193]
	v_ashrrev_i32_e32 v1, 31, v0
	global_load_dwordx4 v[16:19], v[2:3], off
	v_lshlrev_b64 v[0:1], 9, v[0:1]
	v_and_b32_e32 v2, 7, v4
	v_lshl_or_b32 v0, v2, 4, v0
	v_lshl_add_u64 v[0:1], s[30:31], 0, v[0:1]
	global_load_dwordx4 v[20:23], v[0:1], off

; DI void task_nsa(const P& p, int layer, int task, bf16_t* sm, int dm) {
;     ...
;     for (; todo; ++itc) {
;       const int j = __ffsll((long long)todo) - 1;
;       todo &= todo - 1ull;
;       bf16_t* Kl = sm + (itc & 1) * 9216; bf16_t* Vl = Kl + 4608;
;       kv_lstore(R, Kl, Vl);
;       if (todo) kv_gload(R, kg, 128, vg, S_, (__ffsll((long long)todo) - 1) * 64);
;       __syncthreads();
.LBB0_718:
	v_lshl_add_u64 v[2:3], v[0:1], 0, -1
	v_and_b32_e32 v98, v2, v0
	v_mov_b32_e32 v2, v195
	s_bitcmp1_b32 s39, 0
	v_and_b32_e32 v99, v3, v1
	s_cselect_b32 s2, 0x4800, 0
	s_add_i32 s45, s2, 0
	v_cmp_eq_u64_e64 s[2:3], 0, v[98:99]
	v_add_u32_e32 v2, s45, v235
	s_and_b64 vcc, exec, s[2:3]
	s_waitcnt vmcnt(0)
	ds_write_b128 v2, v[80:83]
	ds_write_b128 v2, v[84:87] offset:9216
	s_cbranch_vccnz .LBB0_720
	v_ffbl_b32_e32 v3, v99
	v_ffbl_b32_e32 v2, v98
	v_add_u32_e64 v3, v3, 32 clamp
	v_min_u32_e32 v6, v3, v2
	v_mov_b32_e32 v3, v195
	v_mov_b32_e32 v7, v193
	v_ashrrev_i32_e32 v2, 3, v3
	v_lshl_add_u32 v4, v6, 6, v2
	v_lshlrev_b32_e32 v3, 4, v3
	v_ashrrev_i32_e32 v5, 31, v4
	v_and_b32_e32 v192, 0x70, v3
	v_ashrrev_i32_e32 v3, 31, v2
	v_lshlrev_b64 v[4:5], 8, v[4:5]
	v_lshlrev_b64 v[2:3], 13, v[2:3]
	v_lshl_add_u64 v[4:5], s[0:1], 0, v[4:5]
	v_lshl_add_u64 v[2:3], s[6:7], 0, v[2:3]
	v_lshlrev_b32_e32 v6, 7, v6
	v_lshl_add_u64 v[4:5], v[4:5], 0, v[192:193]
	v_lshl_add_u64 v[2:3], v[2:3], 0, v[6:7]
	v_lshl_add_u64 v[2:3], v[2:3], 0, v[192:193]
	global_load_dwordx4 v[80:83], v[4:5], off
	global_load_dwordx4 v[84:87], v[2:3], off

; DI void task_nsa(const P& p, int layer, int task, bf16_t* sm, int dm) {
;     ...
;     for (int kt = kt_lo; kt <= kt_hi; ++kt, ++itc) {
;       bf16_t* Kl = sm + (itc & 1) * 9216; bf16_t* Vl = Kl + 4608;
;       kv_lstore(R, Kl, Vl);
;       if (kt < kt_hi) kv_gload(R, kg, 128, vg, S_, (kt + 1) * 64);
;       __syncthreads();
.LBB0_808:
	s_bitcmp1_b32 s39, 0
	s_cselect_b32 s0, 0x4800, 0
	v_mov_b32_e32 v0, v195
	s_add_i32 s25, s0, 0
	s_cmp_ge_i32 s45, s35
	s_cselect_b64 s[8:9], -1, 0
	v_add_u32_e32 v0, s25, v235
	s_and_b64 vcc, exec, s[8:9]
	s_waitcnt vmcnt(0)
	ds_write_b128 v0, v[80:83]
	ds_write_b128 v0, v[84:87] offset:9216
	s_cbranch_vccnz .LBB0_810
	v_mov_b32_e32 v1, v195
	s_ashr_i32 s7, s6, 31
	v_ashrrev_i32_e32 v0, 3, v1
	v_add3_u32 v2, s6, v0, 64
	v_lshlrev_b32_e32 v1, 4, v1
	v_ashrrev_i32_e32 v3, 31, v2
	v_and_b32_e32 v192, 0x70, v1
	v_ashrrev_i32_e32 v1, 31, v0
	v_lshlrev_b64 v[2:3], 8, v[2:3]
	v_lshlrev_b64 v[0:1], 13, v[0:1]
	v_lshl_add_u64 v[2:3], s[2:3], 0, v[2:3]
	v_lshl_add_u64 v[0:1], s[4:5], 0, v[0:1]
	v_lshl_add_u64 v[2:3], v[2:3], 0, v[192:193]
	v_lshl_add_u64 v[0:1], s[6:7], 1, v[0:1]
	v_lshl_add_u64 v[0:1], v[0:1], 0, v[192:193]
	global_load_dwordx4 v[80:83], v[2:3], off
	global_load_dwordx4 v[84:87], v[0:1], off offset:128

; DI void task_attnB(const P& p, int layer, int task, bf16_t* sm, int dm) {
;     ...
;   for (int kt = kt_lo; kt <= kt_hi; ++kt) {
;     bf16_t* Kl = sm + (kt & 1) * 9216; bf16_t* Vl = Kl + 4608;
;     kv_lstore(R, Kl, Vl);
;     if (kt < kt_hi) kv_gload(R, kg, 128, vg, S_, (kt + 1) * 64);
;     __syncthreads();
.LBB0_900:
	s_bitcmp1_b32 s30, 0
	s_cselect_b32 s0, 0x4800, 0
	v_mov_b32_e32 v0, v195
	s_add_i32 s31, s0, 0
	s_cmp_ge_i32 s30, s25
	s_cselect_b64 s[8:9], -1, 0
	v_add_u32_e32 v0, s31, v235
	s_and_b64 vcc, exec, s[8:9]
	s_waitcnt vmcnt(0)
	ds_write_b128 v0, v[48:51]
	ds_write_b128 v0, v[52:55] offset:9216
	s_cbranch_vccnz .LBB0_902
	v_mov_b32_e32 v1, v195
	s_ashr_i32 s7, s6, 31
	v_ashrrev_i32_e32 v0, 3, v1
	v_add3_u32 v2, s6, v0, 64
	v_lshlrev_b32_e32 v1, 4, v1
	v_ashrrev_i32_e32 v3, 31, v2
	v_and_b32_e32 v192, 0x70, v1
	v_ashrrev_i32_e32 v1, 31, v0
	v_lshlrev_b64 v[2:3], 8, v[2:3]
	v_lshlrev_b64 v[0:1], 13, v[0:1]
	v_lshl_add_u64 v[2:3], s[2:3], 0, v[2:3]
	v_lshl_add_u64 v[0:1], s[4:5], 0, v[0:1]
	v_lshl_add_u64 v[2:3], v[2:3], 0, v[192:193]
	v_lshl_add_u64 v[0:1], s[6:7], 1, v[0:1]
	v_lshl_add_u64 v[0:1], v[0:1], 0, v[192:193]
	global_load_dwordx4 v[48:51], v[2:3], off
	global_load_dwordx4 v[52:55], v[0:1], off offset:128
